# v022 cache policy + ffn_up acc dump/conv weight loads issued right after the K-loop, tile-top zero-init after stage ds_writes, resid K-loop trailing MFMAs before the drain wait
# baseline (speedup 1.0000x reference)
; DI unsigned pk2(float a, float b) { f32x2 v = {a, b}; bf16x2_t r = __builtin_convertvector(v, bf16x2_t); return __builtin_bit_cast(unsigned, r); }
; DI float silu_f(float g) { return g * rcpf_(1.f + ex2(-g * LOG2E)); }
; static __device__ __forceinline__ void phase_ffn_up(const P& p, int l, char* lds) {
;     ...
; #pragma unroll
;       for (int jj = 0; jj < 4; ++jj) {
;         const int r = (tid >> 3) + 64 * jj, tt = tstart + r;
;         if (r >= 1 && r <= 254 && tt < MEND) {
;           const int pos = tt < MLAT ? (tt & (TLAT - 1)) : ((tt - MLAT) & (TCTX - 1)), slen = tt < MLAT ? TLAT : TCTX;
;           const float fm = pos == 0 ? 0.f : 1.f, fp = pos == slen - 1 ? 0.f : 1.f;
;           const char* rp = tile + r * 528;
;           float o[8];
; #pragma unroll
;           for (int hf = 0; hf < 2; ++hf) {
;             const f32x4 am = *(const f32x4*)(rp - 528 + lca + hf * 16), a0 = *(const f32x4*)(rp + lca + hf * 16), ap = *(const f32x4*)(rp + 528 + lca + hf * 16);
;             const f32x4 gm = *(const f32x4*)(rp - 528 + lcg + hf * 16), g0 = *(const f32x4*)(rp + lcg + hf * 16), gp = *(const f32x4*)(rp + 528 + lcg + hf * 16);
; #pragma unroll
;             for (int e = 0; e < 4; ++e) {
;               const int q = hf * 4 + e;
;               const float ua = wa0[q] * (fm * am[e]) + wa1[q] * a0[e] + wa2[q] * (fp * ap[e]) + ba[q];
;               const float ug = wg0[q] * (fm * gm[e]) + wg1[q] * g0[e] + wg2[q] * (fp * gp[e]) + bg[q];
;               o[q] = silu_f(ug) * ua;
;             }
;           }
;           u32x4 w = {pk2(o[0], o[1]), pk2(o[2], o[3]), pk2(o[4], o[5]), pk2(o[6], o[7])};
;           *(u32x4*)(act + (size_t)tt * DFF + ca0) = w;
.Lwt_done:
	s_and_saveexec_b64 s[20:21], s[22:23]
	s_cbranch_execz .LBB0_1079
	v_add_u32_e32 v159, v151, v150
	v_cmp_gt_i32_e32 vcc, s39, v158
	s_nop 1
	v_cndmask_b32_e32 v114, v235, v236, vcc
	v_and_b32_e32 v115, v114, v158
	v_cmp_eq_u32_e64 s[100:101], 0, v115
	v_cmp_eq_u32_e32 vcc, v115, v114
	s_nop 3
	s_or_b64 s[100:101], s[100:101], vcc
	s_cbranch_scc0 .Lcf_0
	v_add_u32_e32 v159, v151, v150
	v_cmp_gt_i32_e32 vcc, s39, v158
	ds_read_b128 v[136:139], v159 offset:1904
	ds_read_b128 v[160:163], v159 offset:2432
	v_cndmask_b32_e32 v114, v235, v236, vcc
	v_and_b32_e32 v115, v114, v158
	ds_read_b128 v[164:167], v159 offset:2960
	ds_read_b128 v[168:171], v159 offset:1776
	v_cmp_eq_u32_e32 vcc, 0, v115
	s_waitcnt vmcnt(6) lgkmcnt(2)
	v_pk_mul_f32 v[116:117], v[102:103], v[160:161]
	v_pk_mul_f32 v[162:163], v[104:105], v[162:163]
	v_cndmask_b32_e64 v0, 1.0, 0, vcc
	v_cmp_eq_u32_e32 vcc, v115, v114
	v_pk_mul_f32 v[114:115], v[0:1], v[136:137] op_sel_hi:[0,1]
	v_pk_fma_f32 v[114:115], v[98:99], v[114:115], v[116:117]
	v_cndmask_b32_e64 v134, 1.0, 0, vcc
	s_waitcnt lgkmcnt(1)
	v_pk_mul_f32 v[116:117], v[134:135], v[164:165] op_sel_hi:[0,1]
	s_waitcnt vmcnt(3)
	v_pk_fma_f32 v[114:115], v[106:107], v[116:117], v[114:115]
	v_pk_mul_f32 v[138:139], v[0:1], v[138:139] op_sel_hi:[0,1]
	s_waitcnt vmcnt(1)
	v_pk_add_f32 v[136:137], v[110:111], v[114:115]
	v_pk_fma_f32 v[138:139], v[100:101], v[138:139], v[162:163]
	v_mul_f32_e32 v114, 0xbfb8aa3b, v136
	v_mul_f32_e32 v161, 0xbfb8aa3b, v137
	v_exp_f32_e32 v160, v114
	ds_read_b128 v[114:117], v159 offset:1792
	ds_read_b128 v[172:175], v159 offset:2304
	ds_read_b128 v[176:179], v159 offset:2832
	v_exp_f32_e32 v161, v161
	v_pk_mul_f32 v[162:163], v[134:135], v[166:167] op_sel_hi:[0,1]
	v_pk_fma_f32 v[138:139], v[108:109], v[162:163], v[138:139]
	v_add_f32_e32 v160, 1.0, v160
	v_pk_add_f32 v[138:139], v[112:113], v[138:139]
	s_waitcnt lgkmcnt(3)
	v_pk_mul_f32 v[164:165], v[0:1], v[168:169] op_sel_hi:[0,1]
	s_waitcnt lgkmcnt(1)
	v_pk_mul_f32 v[168:169], v[94:95], v[172:173]
	v_add_f32_e32 v161, 1.0, v161
	v_mul_f32_e32 v162, 0xbfb8aa3b, v138
	v_rcp_f32_e32 v160, v160
	v_pk_fma_f32 v[164:165], v[86:87], v[164:165], v[168:169]
	s_waitcnt lgkmcnt(0)
	v_pk_mul_f32 v[168:169], v[134:135], v[176:177] op_sel_hi:[0,1]
	v_rcp_f32_e32 v161, v161
	v_exp_f32_e32 v166, v162
	v_pk_fma_f32 v[164:165], v[90:91], v[168:169], v[164:165]
	v_pk_mul_f32 v[114:115], v[0:1], v[114:115] op_sel_hi:[0,1]
	v_pk_add_f32 v[162:163], v[82:83], v[164:165]
	v_mul_f32_e32 v164, 0xbfb8aa3b, v139
	v_exp_f32_e32 v164, v164
	v_pk_mul_f32 v[136:137], v[136:137], v[160:161]
	v_add_f32_e32 v160, 1.0, v166
	v_pk_mul_f32 v[136:137], v[162:163], v[136:137]
	v_rcp_f32_e32 v172, v160
	v_pk_mul_f32 v[160:161], v[0:1], v[170:171] op_sel_hi:[0,1]
	v_pk_mul_f32 v[162:163], v[96:97], v[174:175]
	v_pk_mul_f32 v[116:117], v[0:1], v[116:117] op_sel_hi:[0,1]
	v_pk_fma_f32 v[160:161], v[88:89], v[160:161], v[162:163]
	v_pk_mul_f32 v[162:163], v[134:135], v[178:179] op_sel_hi:[0,1]
	v_pk_fma_f32 v[168:169], v[92:93], v[162:163], v[160:161]
	v_add_f32_e32 v160, 1.0, v164
	v_rcp_f32_e32 v173, v160
	ds_read_b128 v[160:163], v159 offset:1920
	ds_read_b128 v[164:167], v159 offset:2448
	v_pk_add_f32 v[174:175], v[84:85], v[168:169]
	ds_read_b128 v[168:171], v159 offset:2976
	v_pk_mul_f32 v[138:139], v[138:139], v[172:173]
	s_waitcnt lgkmcnt(2)
	v_pk_mul_f32 v[160:161], v[0:1], v[160:161] op_sel_hi:[0,1]
	s_waitcnt lgkmcnt(1)
	v_pk_mul_f32 v[164:165], v[70:71], v[164:165]
	v_pk_mul_f32 v[138:139], v[174:175], v[138:139]
	v_pk_fma_f32 v[160:161], v[66:67], v[160:161], v[164:165]
	s_waitcnt lgkmcnt(0)
	v_pk_mul_f32 v[164:165], v[134:135], v[168:169] op_sel_hi:[0,1]
	v_pk_fma_f32 v[160:161], v[74:75], v[164:165], v[160:161]
	ds_read_b128 v[172:175], v159 offset:2320
	ds_read_b128 v[176:179], v159 offset:2848
	s_waitcnt vmcnt(0)
	v_pk_add_f32 v[160:161], v[78:79], v[160:161]
	v_pk_mul_f32 v[162:163], v[0:1], v[162:163] op_sel_hi:[0,1]
	v_mul_f32_e32 v164, 0xbfb8aa3b, v160
	v_exp_f32_e32 v164, v164
	s_waitcnt lgkmcnt(1)
	v_pk_mul_f32 v[168:169], v[58:59], v[172:173]
	v_pk_mul_f32 v[166:167], v[72:73], v[166:167]
	v_pk_fma_f32 v[114:115], v[50:51], v[114:115], v[168:169]
	v_add_f32_e32 v159, 1.0, v164
	v_rcp_f32_e32 v164, v159
	v_mul_f32_e32 v159, 0xbfb8aa3b, v161
	v_exp_f32_e32 v159, v159
	s_waitcnt lgkmcnt(0)
	v_pk_mul_f32 v[168:169], v[134:135], v[176:177] op_sel_hi:[0,1]
	v_pk_fma_f32 v[162:163], v[68:69], v[162:163], v[166:167]
	v_pk_mul_f32 v[166:167], v[134:135], v[170:171] op_sel_hi:[0,1]
	v_add_f32_e32 v159, 1.0, v159
	v_rcp_f32_e32 v165, v159
	v_pk_fma_f32 v[114:115], v[54:55], v[168:169], v[114:115]
	v_pk_fma_f32 v[162:163], v[76:77], v[166:167], v[162:163]
	v_pk_add_f32 v[114:115], v[62:63], v[114:115]
	v_pk_add_f32 v[162:163], v[80:81], v[162:163]
	v_pk_mul_f32 v[160:161], v[160:161], v[164:165]
	v_mul_f32_e32 v159, 0xbfb8aa3b, v162
	v_pk_mul_f32 v[160:161], v[114:115], v[160:161]
	v_mul_f32_e32 v115, 0xbfb8aa3b, v163
	v_exp_f32_e32 v159, v159
	v_exp_f32_e32 v115, v115
	v_pk_mul_f32 v[164:165], v[60:61], v[174:175]
	s_movk_i32 s14, 0x1600
	v_add_f32_e32 v114, 1.0, v159
	v_add_f32_e32 v0, 1.0, v115
	v_rcp_f32_e32 v114, v114
	v_rcp_f32_e32 v115, v0
	v_pk_fma_f32 v[116:117], v[52:53], v[116:117], v[164:165]
	v_pk_mul_f32 v[164:165], v[134:135], v[178:179] op_sel_hi:[0,1]
	v_pk_fma_f32 v[116:117], v[56:57], v[164:165], v[116:117]
	v_pk_mul_f32 v[114:115], v[162:163], v[114:115]
	v_pk_add_f32 v[116:117], v[64:65], v[116:117]
	s_nop 0
	v_pk_mul_f32 v[162:163], v[116:117], v[114:115]
	v_cvt_pk_bf16_f32 v114, v136, v137
	v_cvt_pk_bf16_f32 v115, v138, v139
	v_cvt_pk_bf16_f32 v116, v160, v161
	v_cvt_pk_bf16_f32 v117, v162, v163
	v_mad_i64_i32 v[136:137], s[22:23], v158, s14, v[132:133]
	global_store_dwordx4 v[136:137], v[114:117], off sc0 sc1 nt
